# final combine (second code copy) now also waits on its row tile's partial counters and reads the partials with sc1 loads (it ran unsynchronised after the last projection)
# baseline (speedup 1.0000x reference)
.LBB0_1388:
	v_mov_b32_e32 v0, 0
	v_mov_b32_e32 v17, 0
	v_mbcnt_lo_u32_b32 v0, -1, v0
	v_mbcnt_hi_u32_b32 v0, -1, v0
	v_add_u32_e32 v1, s86, v0
	s_nop 0
	v_readfirstlane_b32 s0, v1
	s_ashr_i32 s0, s0, 6
	s_add_i32 s0, s0, s55
	s_cmpk_gt_i32 s0, 0x7ff
	s_cbranch_scc1 .LBB0_1395
	s_load_dwordx2 s[8:9], s[66:67], 0x100
	v_mov_b32_e32 v1, 0x20178
	ds_read_b32 v2, v1
	v_readlane_b32 s10, v255, 0
	s_nop 3
	s_lshr_b32 s10, s10, 3
	s_lshl_b32 s10, s10, 5
	s_add_u32 s10, s10, 0xe803a00
	s_waitcnt lgkmcnt(0)
	s_add_u32 s8, s8, s10
	s_addc_u32 s9, s9, 0
.Lfc_poll:
	global_load_dword v3, v17, s[8:9] sc1
	s_waitcnt vmcnt(0)
	v_cmp_le_u32_e32 vcc, v2, v3
	s_cbranch_vccnz .Lfc_go
	s_sleep 2
	s_branch .Lfc_poll
.Lfc_go:
	s_load_dwordx4 s[4:7], s[66:67], 0xf8
	v_lshlrev_b32_e32 v1, 2, v0
	v_and_b32_e32 v2, 0xfc, v1
	v_lshlrev_b32_e32 v16, 2, v2
	v_lshlrev_b32_e32 v10, 1, v2
	s_waitcnt lgkmcnt(0)
	s_add_u32 s20, s4, 0x1000000
	s_addc_u32 s21, s5, 0
	s_lshl_b32 s2, s0, 2
	v_mov_b32_e32 v11, v17
	v_lshl_add_u64 v[4:5], s[6:7], 0, v[16:17]
	s_mov_b64 s[0:1], 0xe827000
	s_cmp_lg_u64 s[4:5], 0
	v_lshl_add_u64 v[10:11], s[6:7], 0, v[10:11]
	s_mov_b64 s[8:9], 0xa800000
	v_lshl_add_u64 v[18:19], v[4:5], 0, s[0:1]
	s_cselect_b64 s[0:1], -1, 0
	v_lshl_add_u64 v[20:21], v[10:11], 0, s[8:9]
	s_mov_b64 s[8:9], 0x9800000
	s_ashr_i32 s3, s2, 31
	v_lshl_add_u64 v[22:23], v[10:11], 0, s[8:9]
	s_lshl_b64 s[8:9], s[2:3], 12
	v_lshl_add_u64 v[24:25], s[4:5], 0, v[16:17]
	s_add_u32 s4, s4, s8
	s_addc_u32 s5, s5, s9
	s_lshl_b64 s[8:9], s[2:3], 11
	v_and_b32_e32 v0, 63, v0
	s_add_u32 s6, s6, s8
	v_lshlrev_b32_e32 v16, 4, v0
	v_lshlrev_b32_e32 v0, 3, v0
	v_mov_b32_e32 v1, v17
	s_addc_u32 s7, s7, s9
	v_lshl_add_u64 v[0:1], s[6:7], 0, v[0:1]
	s_mov_b64 s[6:7], 0x9800800
	v_or_b32_e32 v4, 0x100, v2
	v_or_b32_e32 v6, 0x200, v2
	v_or_b32_e32 v8, 0x300, v2
	v_lshl_add_u64 v[26:27], v[0:1], 0, s[6:7]
	v_cndmask_b32_e64 v0, 0, 1, s[0:1]
	s_movk_i32 s22, 0x1000
	s_mov_b32 s7, 0
	v_cmp_ne_u32_e64 s[0:1], 1, v0
	s_mov_b32 s23, 0x1001000
	v_lshlrev_b32_e32 v60, 2, v8
	v_lshlrev_b32_e32 v61, 2, v6
	v_lshlrev_b32_e32 v62, 2, v4
	v_lshlrev_b32_e32 v63, 2, v2
	s_mov_b32 s24, 0x1000000
	s_movk_i32 s25, 0x2000
	s_movk_i32 s26, 0x3000
	s_branch .LBB0_1391

.LBB0_1393:
	s_and_b64 vcc, exec, s[0:1]
	s_cbranch_vccnz .LBB0_1390
	s_lshr_b32 s6, s6, 11
	s_mulk_i32 s6, 0x2400
	s_lshl_b64 s[8:9], s[18:19], 12
	s_addk_i32 s6, 0x2400
	s_and_b64 s[10:11], exec, s[10:11]
	s_cselect_b32 s6, 0, s6
	s_add_u32 s10, s16, 0x3000
	s_addc_u32 s11, s17, 0
	s_add_u32 s12, s16, 0x2000
	s_addc_u32 s13, s17, 0
	s_add_u32 s14, s16, 0x1000
	v_lshl_add_u64 v[28:29], s[6:7], 2, v[18:19]
	s_addc_u32 s15, s17, 0
	s_lshl_b64 s[18:19], s[18:19], 11
	global_load_dwordx4 v[0:3], v[28:29], off offset:3072
	global_load_dwordx4 v[4:7], v[28:29], off offset:2048
	global_load_dwordx4 v[8:11], v[28:29], off offset:1024
	global_load_dwordx4 v[12:15], v[28:29], off
	v_lshl_add_u64 v[28:29], v[22:23], 0, s[18:19]
	global_load_dwordx2 v[36:37], v[28:29], off sc1
	v_lshl_add_u64 v[30:31], v[20:21], 0, s[18:19]
	global_load_dwordx2 v[48:49], v[30:31], off sc1
	global_load_dwordx2 v[52:53], v[28:29], off offset:512 sc1
	global_load_dwordx2 v[54:55], v[30:31], off offset:512 sc1
	global_load_dwordx2 v[56:57], v[28:29], off offset:1024 sc1
	global_load_dwordx2 v[58:59], v[30:31], off offset:1024 sc1
	global_load_dwordx4 v[42:45], v63, s[16:17]
	global_load_dwordx4 v[64:67], v63, s[16:17] offset:1024
	global_load_dwordx4 v[68:71], v63, s[16:17] offset:2048
	global_load_dwordx2 v[96:97], v[28:29], off offset:1536 sc1
	global_load_dwordx4 v[72:75], v63, s[16:17] offset:3072
	global_load_dwordx2 v[98:99], v[30:31], off offset:1536 sc1
	v_add_co_u32_e32 v92, vcc, s23, v26
	v_lshl_add_u64 v[144:145], v[24:25], 0, s[8:9]
	s_nop 0
	v_addc_co_u32_e32 v93, vcc, 0, v27, vcc
	v_add_co_u32_e32 v94, vcc, s22, v26
	s_waitcnt vmcnt(15)
	v_pk_mul_f32 v[28:29], v[2:3], 0.5 op_sel_hi:[1,0]
	v_addc_co_u32_e32 v95, vcc, 0, v27, vcc
	v_add_co_u32_e32 v100, vcc, s24, v26
	v_pk_mul_f32 v[30:31], v[0:1], 0.5 op_sel_hi:[1,0]
	s_nop 0
	v_addc_co_u32_e32 v101, vcc, 0, v27, vcc
	global_load_dwordx2 v[112:113], v[26:27], off sc1
	global_load_dwordx2 v[114:115], v[26:27], off offset:1536 sc1
	global_load_dwordx2 v[116:117], v[26:27], off offset:1024 sc1
	global_load_dwordx2 v[118:119], v[26:27], off offset:512 sc1
	global_load_dwordx2 v[120:121], v[100:101], off offset:1536 sc1
	global_load_dwordx2 v[122:123], v[100:101], off offset:1024 sc1
	global_load_dwordx2 v[124:125], v[100:101], off offset:512 sc1
	global_load_dwordx2 v[126:127], v[100:101], off sc1
	global_load_dwordx4 v[76:79], v63, s[14:15]
	global_load_dwordx4 v[80:83], v62, s[14:15]
	global_load_dwordx4 v[84:87], v61, s[14:15]
	s_waitcnt vmcnt(25)
	v_pk_mul_f32 v[32:33], v[6:7], 0.5 op_sel_hi:[1,0]
	v_pk_mul_f32 v[34:35], v[4:5], 0.5 op_sel_hi:[1,0]
	s_waitcnt vmcnt(22)
	v_lshlrev_b32_e32 v0, 16, v36
	v_and_b32_e32 v1, 0xffff0000, v36
	v_lshlrev_b32_e32 v2, 16, v37
	v_and_b32_e32 v3, 0xffff0000, v37
	s_waitcnt vmcnt(21)
	v_lshlrev_b32_e32 v4, 16, v48
	v_and_b32_e32 v5, 0xffff0000, v48
	v_lshlrev_b32_e32 v6, 16, v49
	v_and_b32_e32 v7, 0xffff0000, v49
	v_pk_mul_f32 v[46:47], v[14:15], 0.5 op_sel_hi:[1,0]
	v_pk_mul_f32 v[50:51], v[12:13], 0.5 op_sel_hi:[1,0]
	s_waitcnt vmcnt(19)
	v_lshlrev_b32_e32 v12, 16, v54
	v_and_b32_e32 v13, 0xffff0000, v54
	v_lshlrev_b32_e32 v14, 16, v55
	v_and_b32_e32 v15, 0xffff0000, v55
	s_waitcnt vmcnt(18)
	v_lshlrev_b32_e32 v48, 16, v57
	v_and_b32_e32 v49, 0xffff0000, v57
	s_waitcnt vmcnt(17)
	v_lshlrev_b32_e32 v54, 16, v59
	v_and_b32_e32 v55, 0xffff0000, v59
	v_pk_add_f32 v[2:3], v[2:3], v[6:7]
	v_pk_add_f32 v[0:1], v[0:1], v[4:5]
	v_pk_mul_f32 v[38:39], v[10:11], 0.5 op_sel_hi:[1,0]
	v_pk_mul_f32 v[40:41], v[8:9], 0.5 op_sel_hi:[1,0]
	v_lshlrev_b32_e32 v8, 16, v52
	v_and_b32_e32 v9, 0xffff0000, v52
	v_lshlrev_b32_e32 v10, 16, v53
	v_and_b32_e32 v11, 0xffff0000, v53
	v_lshlrev_b32_e32 v102, 16, v56
	v_and_b32_e32 v103, 0xffff0000, v56
	v_lshlrev_b32_e32 v104, 16, v58
	v_and_b32_e32 v105, 0xffff0000, v58
	s_waitcnt vmcnt(16)
	v_pk_fma_f32 v[88:89], v[50:51], v[0:1], v[42:43]
	v_pk_fma_f32 v[90:91], v[46:47], v[2:3], v[44:45]
	global_load_dwordx2 v[36:37], v[92:93], off offset:1536 sc1
	global_load_dwordx2 v[44:45], v[92:93], off offset:1024 sc1
	global_load_dwordx2 v[52:53], v[92:93], off offset:512 sc1
	global_load_dwordx2 v[56:57], v[92:93], off sc1
	v_pk_add_f32 v[0:1], v[54:55], v[48:49]
	global_load_dwordx2 v[42:43], v[94:95], off offset:1536 sc1
	global_load_dwordx2 v[48:49], v[94:95], off offset:1024 sc1
	global_load_dwordx2 v[54:55], v[94:95], off offset:512 sc1
	global_load_dwordx2 v[58:59], v[94:95], off sc1
	v_pk_add_f32 v[4:5], v[14:15], v[10:11]
	global_load_dwordx4 v[92:95], v60, s[14:15]
	global_load_dwordx2 v[128:129], v[26:27], off offset:3584 sc1
	global_load_dwordx2 v[130:131], v[26:27], off offset:3072 sc1
	global_load_dwordx2 v[132:133], v[26:27], off offset:2560 sc1
	global_load_dwordx2 v[134:135], v[26:27], off offset:2048 sc1
	global_load_dwordx2 v[136:137], v[100:101], off offset:3584 sc1
	global_load_dwordx2 v[138:139], v[100:101], off offset:3072 sc1
	global_load_dwordx2 v[140:141], v[100:101], off offset:2560 sc1
	global_load_dwordx2 v[142:143], v[100:101], off offset:2048 sc1
	v_pk_add_f32 v[6:7], v[12:13], v[8:9]
	v_pk_add_f32 v[2:3], v[104:105], v[102:103]
	s_waitcnt vmcnt(32)
	v_pk_fma_f32 v[64:65], v[40:41], v[6:7], v[64:65]
	v_pk_fma_f32 v[66:67], v[38:39], v[4:5], v[66:67]
	s_waitcnt vmcnt(31)
	v_pk_fma_f32 v[68:69], v[34:35], v[2:3], v[68:69]
	v_pk_fma_f32 v[70:71], v[32:33], v[0:1], v[70:71]
	s_waitcnt vmcnt(30)
	v_lshlrev_b32_e32 v0, 16, v96
	v_and_b32_e32 v1, 0xffff0000, v96
	v_lshlrev_b32_e32 v2, 16, v97
	v_and_b32_e32 v3, 0xffff0000, v97
	s_waitcnt vmcnt(28)
	v_lshlrev_b32_e32 v4, 16, v98
	v_and_b32_e32 v5, 0xffff0000, v98
	v_lshlrev_b32_e32 v6, 16, v99
	v_and_b32_e32 v7, 0xffff0000, v99
	v_pk_add_f32 v[2:3], v[6:7], v[2:3]
	v_pk_add_f32 v[0:1], v[4:5], v[0:1]
	global_load_dwordx4 v[96:99], v63, s[12:13]
	v_pk_fma_f32 v[72:73], v[30:31], v[0:1], v[72:73]
	v_pk_fma_f32 v[74:75], v[28:29], v[2:3], v[74:75]
	global_load_dwordx4 v[4:7], v61, s[10:11]
	global_load_dwordx4 v[12:15], v63, s[10:11]
	global_load_dwordx4 v[100:103], v61, s[12:13]
	global_load_dwordx4 v[0:3], v60, s[10:11]
	global_load_dwordx4 v[104:107], v60, s[12:13]
	global_load_dwordx4 v[8:11], v62, s[10:11]
	global_load_dwordx4 v[108:111], v62, s[12:13]
	s_nop 0
	global_store_dwordx4 v[144:145], v[88:91], off
	global_store_dwordx4 v[144:145], v[64:67], off offset:1024
	global_store_dwordx4 v[144:145], v[68:71], off offset:2048
	global_store_dwordx4 v[144:145], v[72:75], off offset:3072
	s_waitcnt vmcnt(39)
	v_lshlrev_b32_e32 v64, 16, v112
	v_and_b32_e32 v65, 0xffff0000, v112
	v_lshlrev_b32_e32 v66, 16, v113
	v_and_b32_e32 v67, 0xffff0000, v113
	s_waitcnt vmcnt(33)
	v_lshlrev_b32_e32 v72, 16, v124
	s_waitcnt vmcnt(32)
	v_lshlrev_b32_e32 v68, 16, v126
	v_and_b32_e32 v69, 0xffff0000, v126
	v_pk_add_f32 v[64:65], v[68:69], v[64:65]
	v_lshlrev_b32_e32 v68, 16, v118
	v_and_b32_e32 v69, 0xffff0000, v118
	v_and_b32_e32 v73, 0xffff0000, v124
	v_lshlrev_b32_e32 v70, 16, v127
	v_and_b32_e32 v71, 0xffff0000, v127
	s_waitcnt vmcnt(31)
	v_pk_fma_f32 v[64:65], v[50:51], v[64:65], v[76:77]
	v_pk_add_f32 v[68:69], v[72:73], v[68:69]
	v_lshlrev_b32_e32 v72, 16, v116
	v_and_b32_e32 v73, 0xffff0000, v116
	v_lshlrev_b32_e32 v76, 16, v122
	v_and_b32_e32 v77, 0xffff0000, v122
	v_pk_add_f32 v[66:67], v[70:71], v[66:67]
	v_lshlrev_b32_e32 v70, 16, v119
	v_and_b32_e32 v71, 0xffff0000, v119
	v_lshlrev_b32_e32 v74, 16, v125
	v_and_b32_e32 v75, 0xffff0000, v125
	v_pk_add_f32 v[72:73], v[76:77], v[72:73]
	v_pk_fma_f32 v[66:67], v[46:47], v[66:67], v[78:79]
	v_pk_add_f32 v[70:71], v[74:75], v[70:71]
	s_waitcnt vmcnt(30)
	v_pk_fma_f32 v[68:69], v[40:41], v[68:69], v[80:81]
	v_lshlrev_b32_e32 v74, 16, v117
	v_and_b32_e32 v75, 0xffff0000, v117
	v_lshlrev_b32_e32 v78, 16, v123
	v_and_b32_e32 v79, 0xffff0000, v123
	s_waitcnt vmcnt(29)
	v_pk_fma_f32 v[72:73], v[34:35], v[72:73], v[84:85]
	v_lshlrev_b32_e32 v76, 16, v114
	v_and_b32_e32 v77, 0xffff0000, v114
	v_lshlrev_b32_e32 v80, 16, v120
	v_and_b32_e32 v81, 0xffff0000, v120
	v_lshl_add_u64 v[84:85], s[4:5], 0, v[16:17]
	v_pk_fma_f32 v[70:71], v[38:39], v[70:71], v[82:83]
	v_pk_add_f32 v[74:75], v[78:79], v[74:75]
	v_lshlrev_b32_e32 v78, 16, v115
	v_and_b32_e32 v79, 0xffff0000, v115
	v_lshlrev_b32_e32 v82, 16, v121
	v_and_b32_e32 v83, 0xffff0000, v121
	v_pk_add_f32 v[76:77], v[80:81], v[76:77]
	v_add_co_u32_e32 v80, vcc, s22, v84
	v_pk_add_f32 v[78:79], v[82:83], v[78:79]
	s_nop 0
	v_addc_co_u32_e32 v81, vcc, 0, v85, vcc
	v_pk_fma_f32 v[74:75], v[32:33], v[74:75], v[86:87]
	s_waitcnt vmcnt(20)
	v_pk_fma_f32 v[78:79], v[28:29], v[78:79], v[94:95]
	v_pk_fma_f32 v[76:77], v[30:31], v[76:77], v[92:93]
	global_store_dwordx4 v[80:81], v[68:71], off offset:1024
	global_store_dwordx4 v[80:81], v[72:75], off offset:2048
	global_store_dwordx4 v[80:81], v[76:79], off offset:3072
	s_waitcnt vmcnt(19)
	v_lshlrev_b32_e32 v68, 16, v134
	v_and_b32_e32 v69, 0xffff0000, v134
	s_waitcnt vmcnt(15)
	v_lshlrev_b32_e32 v72, 16, v142
	v_and_b32_e32 v73, 0xffff0000, v142
	v_lshlrev_b32_e32 v70, 16, v135
	v_and_b32_e32 v71, 0xffff0000, v135
	v_lshlrev_b32_e32 v74, 16, v143
	v_and_b32_e32 v75, 0xffff0000, v143
	v_pk_add_f32 v[68:69], v[72:73], v[68:69]
	v_lshlrev_b32_e32 v72, 16, v132
	v_and_b32_e32 v73, 0xffff0000, v132
	v_lshlrev_b32_e32 v76, 16, v140
	v_and_b32_e32 v77, 0xffff0000, v140
	v_pk_add_f32 v[70:71], v[74:75], v[70:71]
	v_lshlrev_b32_e32 v74, 16, v133
	v_and_b32_e32 v75, 0xffff0000, v133
	v_lshlrev_b32_e32 v78, 16, v141
	v_and_b32_e32 v79, 0xffff0000, v141
	v_pk_add_f32 v[72:73], v[76:77], v[72:73]
	v_lshlrev_b32_e32 v76, 16, v130
	v_and_b32_e32 v77, 0xffff0000, v130
	v_lshlrev_b32_e32 v80, 16, v138
	v_and_b32_e32 v81, 0xffff0000, v138
	v_pk_add_f32 v[74:75], v[78:79], v[74:75]
	v_lshlrev_b32_e32 v78, 16, v131
	v_and_b32_e32 v79, 0xffff0000, v131
	v_lshlrev_b32_e32 v82, 16, v139
	v_and_b32_e32 v83, 0xffff0000, v139
	v_pk_add_f32 v[76:77], v[80:81], v[76:77]
	v_lshlrev_b32_e32 v80, 16, v128
	v_and_b32_e32 v81, 0xffff0000, v128
	v_lshlrev_b32_e32 v86, 16, v136
	v_and_b32_e32 v87, 0xffff0000, v136
	v_pk_add_f32 v[78:79], v[82:83], v[78:79]
	v_lshlrev_b32_e32 v82, 16, v129
	v_and_b32_e32 v83, 0xffff0000, v129
	v_lshlrev_b32_e32 v88, 16, v137
	v_and_b32_e32 v89, 0xffff0000, v137
	v_pk_add_f32 v[80:81], v[86:87], v[80:81]
	v_add_co_u32_e32 v86, vcc, s25, v84
	v_pk_add_f32 v[82:83], v[88:89], v[82:83]
	s_nop 0
	v_addc_co_u32_e32 v87, vcc, 0, v85, vcc
	s_waitcnt vmcnt(14)
	v_pk_fma_f32 v[70:71], v[46:47], v[70:71], v[98:99]
	v_pk_fma_f32 v[68:69], v[50:51], v[68:69], v[96:97]
	s_waitcnt vmcnt(7)
	v_pk_fma_f32 v[74:75], v[38:39], v[74:75], v[110:111]
	v_pk_fma_f32 v[72:73], v[40:41], v[72:73], v[108:109]
	v_pk_fma_f32 v[78:79], v[32:33], v[78:79], v[102:103]
	v_pk_fma_f32 v[76:77], v[34:35], v[76:77], v[100:101]
	v_pk_fma_f32 v[82:83], v[28:29], v[82:83], v[106:107]
	v_pk_fma_f32 v[80:81], v[30:31], v[80:81], v[104:105]
	global_store_dwordx4 v[86:87], v[64:67], off offset:-4096
	global_store_dwordx4 v[86:87], v[68:71], off
	global_store_dwordx4 v[86:87], v[72:75], off offset:1024
	global_store_dwordx4 v[86:87], v[76:79], off offset:2048
	global_store_dwordx4 v[86:87], v[80:83], off offset:3072
	v_lshlrev_b32_e32 v64, 16, v58
	v_and_b32_e32 v65, 0xffff0000, v58
	v_lshlrev_b32_e32 v58, 16, v59
	v_and_b32_e32 v59, 0xffff0000, v59
	v_lshlrev_b32_e32 v66, 16, v56
	v_and_b32_e32 v67, 0xffff0000, v56
	v_lshlrev_b32_e32 v56, 16, v57
	v_and_b32_e32 v57, 0xffff0000, v57
	v_pk_add_f32 v[56:57], v[56:57], v[58:59]
	v_pk_add_f32 v[58:59], v[66:67], v[64:65]
	v_pk_fma_f32 v[14:15], v[46:47], v[56:57], v[14:15]
	v_add_co_u32_e32 v46, vcc, s26, v84
	v_pk_fma_f32 v[12:13], v[50:51], v[58:59], v[12:13]
	s_nop 0
	v_addc_co_u32_e32 v47, vcc, 0, v85, vcc
	global_store_dwordx4 v[46:47], v[12:15], off
	v_lshlrev_b32_e32 v50, 16, v52
	v_and_b32_e32 v51, 0xffff0000, v52
	v_lshlrev_b32_e32 v12, 16, v54
	v_and_b32_e32 v13, 0xffff0000, v54
	v_lshlrev_b32_e32 v14, 16, v55
	v_and_b32_e32 v15, 0xffff0000, v55
	v_lshlrev_b32_e32 v52, 16, v53
	v_and_b32_e32 v53, 0xffff0000, v53
	v_pk_add_f32 v[14:15], v[52:53], v[14:15]
	v_pk_add_f32 v[12:13], v[50:51], v[12:13]
	v_pk_fma_f32 v[10:11], v[38:39], v[14:15], v[10:11]
	v_pk_fma_f32 v[8:9], v[40:41], v[12:13], v[8:9]
	global_store_dwordx4 v[46:47], v[8:11], off offset:1024
	v_lshlrev_b32_e32 v12, 16, v44
	v_and_b32_e32 v13, 0xffff0000, v44
	v_lshlrev_b32_e32 v8, 16, v48
	v_and_b32_e32 v9, 0xffff0000, v48
	v_lshlrev_b32_e32 v10, 16, v49
	v_and_b32_e32 v11, 0xffff0000, v49
	v_lshlrev_b32_e32 v14, 16, v45
	v_and_b32_e32 v15, 0xffff0000, v45
	v_pk_add_f32 v[10:11], v[14:15], v[10:11]
	v_pk_add_f32 v[8:9], v[12:13], v[8:9]
	v_pk_fma_f32 v[6:7], v[32:33], v[10:11], v[6:7]
	v_pk_fma_f32 v[4:5], v[34:35], v[8:9], v[4:5]
	global_store_dwordx4 v[46:47], v[4:7], off offset:2048
	v_lshlrev_b32_e32 v8, 16, v36
	v_and_b32_e32 v9, 0xffff0000, v36
	v_lshlrev_b32_e32 v4, 16, v42
	v_and_b32_e32 v5, 0xffff0000, v42
	v_lshlrev_b32_e32 v6, 16, v43
	v_and_b32_e32 v7, 0xffff0000, v43
	v_lshlrev_b32_e32 v10, 16, v37
	v_and_b32_e32 v11, 0xffff0000, v37
	v_pk_add_f32 v[6:7], v[10:11], v[6:7]
	v_pk_add_f32 v[4:5], v[8:9], v[4:5]
	v_pk_fma_f32 v[2:3], v[28:29], v[6:7], v[2:3]
	v_pk_fma_f32 v[0:1], v[30:31], v[4:5], v[0:1]
	global_store_dwordx4 v[46:47], v[0:3], off offset:3072
	s_branch .LBB0_1390
